# norm phase 1 row loop: the 9 serialized adaLN/gamma parameter loads issued up front with the row loads (one vmcnt(0) before the first store)
# speedup vs baseline: 1.0088x; 1.0087x over previous
; DI unsigned pack2(float a, float b) { f2_t v = {a, b}; return __builtin_bit_cast(unsigned, __builtin_convertvector(v, bf2_t)); }
; DI int otid() { int t = threadIdx.x; asm volatile("" : "+v"(t)); return t; }
; template <int MODE>
; DI void phase_norm(const float* xin, const float* g, const float* modl, int sh_off, int sc_off, u16* hout, float* fout) {
;   const int tid = otid(); const int lane = tid & 63, w = tid >> 6;
;   for (int row = blockIdx.x * NWAVE + w; row < NTOK; row += gridDim.x * NWAVE) {
;     const int b = row >> 14;
;     const float4* xr = (const float4*)(xin + (size_t)row * 1024);
;     float4 v[4];
; #pragma unroll
;     for (int i = 0; i < 4; ++i) v[i] = xr[lane + i * 64];
;     float ss = 0.f;
; #pragma unroll
;     for (int i = 0; i < 4; ++i) ss += v[i].x * v[i].x + v[i].y * v[i].y + v[i].z * v[i].z + v[i].w * v[i].w;
;     ss = wave_sum(ss);
;     const float inv = rsqrtf(ss * (1.f / 1024.f) + 1e-6f);
; #pragma unroll
;     for (int i = 0; i < 4; ++i) {
;       const int col = (lane + i * 64) * 4;
;       const float4 g4 = *(const float4*)(g + col);
;       if (MODE == 0) {
;         const float4 sc4 = *(const float4*)(modl + b * 6144 + sc_off + col);
;         const float4 sh4 = *(const float4*)(modl + b * 6144 + sh_off + col);
;         float y0 = v[i].x * inv * g4.x * (1.f + sc4.x) + sh4.x;
;         float y1 = v[i].y * inv * g4.y * (1.f + sc4.y) + sh4.y;
;         float y2 = v[i].z * inv * g4.z * (1.f + sc4.z) + sh4.z;
;         float y3 = v[i].w * inv * g4.w * (1.f + sc4.w) + sh4.w;
;         *(uint2*)(hout + (size_t)row * 1024 + col) = make_uint2(pack2(y0, y1), pack2(y2, y3));
.LBB0_55:
	v_ashrrev_i32_e32 v3, 31, v2
	v_lshlrev_b64 v[38:39], 12, v[2:3]
	v_lshl_add_u64 v[50:51], v[6:7], 0, v[38:39]
	global_load_dwordx4 v[38:41], v[50:51], off
	global_load_dwordx4 v[42:45], v[50:51], off offset:1024
	global_load_dwordx4 v[46:49], v[50:51], off offset:2048
	s_nop 0
	global_load_dwordx4 v[50:53], v[50:51], off offset:3072
	v_ashrrev_i32_e32 v54, 14, v2
	v_mul_i32_i24_e32 v54, 0x1800, v54
	v_ashrrev_i32_e32 v55, 31, v54
	v_lshl_add_u64 v[62:63], v[54:55], 2, s[26:27]
	s_mov_b64 s[6:7], 0x1000
	v_lshl_add_u64 v[66:67], v[62:63], 0, s[6:7]
	v_lshl_add_u64 v[54:55], v[66:67], 0, v[0:1]
	global_load_dwordx4 v[54:57], v[54:55], off
	s_nop 0
	global_load_dwordx4 v[58:61], v[4:5], off
	v_lshl_add_u64 v[68:69], v[62:63], 0, v[0:1]
	global_load_dwordx4 v[62:65], v[68:69], off
	v_lshl_add_u64 v[122:123], v[66:67], 0, v[10:11]
	v_lshl_add_u64 v[124:125], v[66:67], 0, v[12:13]
	v_lshl_add_u64 v[126:127], v[66:67], 0, v[14:15]
	global_load_dwordx4 v[86:89], v[4:5], off offset:1024
	global_load_dwordx4 v[90:93], v[122:123], off
	global_load_dwordx4 v[94:97], v[68:69], off offset:1024
	global_load_dwordx4 v[98:101], v[4:5], off offset:2048
	global_load_dwordx4 v[102:105], v[124:125], off
	global_load_dwordx4 v[106:109], v[68:69], off offset:2048
	global_load_dwordx4 v[110:113], v[4:5], off offset:3072
	global_load_dwordx4 v[114:117], v[126:127], off
	global_load_dwordx4 v[118:121], v[68:69], off offset:3072
	s_waitcnt vmcnt(15)
	v_mov_b32_e32 v76, v39
	s_waitcnt vmcnt(14)
	v_mov_b32_e32 v77, v43
	v_mov_b32_e32 v74, v38
	v_mov_b32_e32 v75, v42
	s_waitcnt vmcnt(13)
	v_mov_b32_e32 v84, v47
	s_waitcnt vmcnt(12)
	v_mov_b32_e32 v85, v51
	v_pk_mul_f32 v[76:77], v[76:77], v[76:77]
	v_mov_b32_e32 v70, v40
	v_mov_b32_e32 v71, v44
	v_mov_b32_e32 v82, v46
	v_mov_b32_e32 v83, v50
	v_pk_mul_f32 v[84:85], v[84:85], v[84:85]
	v_pk_fma_f32 v[74:75], v[74:75], v[74:75], v[76:77]
	v_mov_b32_e32 v72, v41
	v_mov_b32_e32 v73, v45
	v_mov_b32_e32 v78, v48
	v_mov_b32_e32 v79, v52
	v_pk_fma_f32 v[76:77], v[82:83], v[82:83], v[84:85]
	v_pk_fma_f32 v[70:71], v[70:71], v[70:71], v[74:75]
	v_mov_b32_e32 v80, v49
	v_mov_b32_e32 v81, v53
	v_pk_fma_f32 v[74:75], v[78:79], v[78:79], v[76:77]
	v_pk_fma_f32 v[70:71], v[72:73], v[72:73], v[70:71]
	v_pk_fma_f32 v[72:73], v[80:81], v[80:81], v[74:75]
	v_add_f32_e32 v70, v70, v71
	v_add_f32_e32 v70, v70, v72
	v_add_f32_e32 v70, v70, v73
	ds_bpermute_b32 v71, v32, v70
	s_waitcnt vmcnt(11)
	v_pk_add_f32 v[54:55], v[54:55], 1.0 op_sel_hi:[1,0]
	v_pk_add_f32 v[56:57], v[56:57], 1.0 op_sel_hi:[1,0]
	s_waitcnt lgkmcnt(0)
	v_add_f32_e32 v70, v70, v71
	ds_bpermute_b32 v71, v33, v70
	s_waitcnt lgkmcnt(0)
	v_add_f32_e32 v70, v70, v71
	ds_bpermute_b32 v71, v34, v70
	s_waitcnt lgkmcnt(0)
	v_add_f32_e32 v70, v70, v71
	ds_bpermute_b32 v71, v35, v70
	s_waitcnt lgkmcnt(0)
	v_add_f32_e32 v70, v70, v71
	ds_bpermute_b32 v71, v36, v70
	s_waitcnt lgkmcnt(0)
	v_add_f32_e32 v72, v70, v71
	ds_bpermute_b32 v73, v37, v72
	v_lshlrev_b64 v[70:71], 11, v[2:3]
	v_lshl_add_u64 v[70:71], v[8:9], 0, v[70:71]
	v_add_u32_e32 v2, s3, v2
	s_waitcnt lgkmcnt(0)
	v_add_f32_e32 v3, v72, v73
	v_fmamk_f32 v3, v3, 0x3a800000, v225
	v_mul_f32_e32 v72, 0x4b800000, v3
	v_cmp_gt_f32_e32 vcc, s33, v3
	s_nop 1
	v_cndmask_b32_e32 v3, v3, v72, vcc
	v_rsq_f32_e32 v3, v3
	v_lshl_add_u64 v[72:73], v[66:67], 0, v[10:11]
	v_mul_f32_e32 v74, 0x45800000, v3
	v_cndmask_b32_e32 v74, v3, v74, vcc
	v_pk_mul_f32 v[38:39], v[38:39], v[74:75] op_sel_hi:[1,0]
	v_pk_mul_f32 v[40:41], v[40:41], v[74:75] op_sel_hi:[1,0]
	s_waitcnt vmcnt(10)
	v_pk_mul_f32 v[38:39], v[58:59], v[38:39]
	v_pk_mul_f32 v[40:41], v[60:61], v[40:41]
	s_waitcnt vmcnt(0)
	v_pk_fma_f32 v[38:39], v[54:55], v[38:39], v[62:63]
	v_pk_fma_f32 v[40:41], v[56:57], v[40:41], v[64:65]
	v_cvt_pk_bf16_f32 v38, v38, v39
	v_cvt_pk_bf16_f32 v39, v40, v41
	global_store_dwordx2 v[70:71], v[38:39], off
	s_nop 0
	v_pk_mul_f32 v[42:43], v[42:43], v[74:75] op_sel_hi:[1,0]
	v_pk_mul_f32 v[44:45], v[44:45], v[74:75] op_sel_hi:[1,0]
	v_lshl_add_u64 v[62:63], v[66:67], 0, v[12:13]
	v_pk_mul_f32 v[46:47], v[46:47], v[74:75] op_sel_hi:[1,0]
	v_pk_mul_f32 v[48:49], v[48:49], v[74:75] op_sel_hi:[1,0]
	v_pk_mul_f32 v[50:51], v[50:51], v[74:75] op_sel_hi:[1,0]
	v_pk_mul_f32 v[52:53], v[52:53], v[74:75] op_sel_hi:[1,0]
	v_cmp_lt_i32_e32 vcc, s94, v2
	s_or_b64 s[28:29], vcc, s[28:29]
	v_pk_mul_f32 v[38:39], v[42:43], v[86:87]
	v_pk_add_f32 v[42:43], v[90:91], 1.0 op_sel_hi:[1,0]
	v_pk_mul_f32 v[40:41], v[44:45], v[88:89]
	v_pk_add_f32 v[44:45], v[92:93], 1.0 op_sel_hi:[1,0]
	v_pk_fma_f32 v[38:39], v[38:39], v[42:43], v[94:95]
	v_pk_fma_f32 v[40:41], v[40:41], v[44:45], v[96:97]
	v_cvt_pk_bf16_f32 v38, v38, v39
	v_cvt_pk_bf16_f32 v39, v40, v41
	global_store_dwordx2 v[70:71], v[38:39], off offset:512
	s_nop 0
	v_lshl_add_u64 v[58:59], v[66:67], 0, v[14:15]
	v_pk_mul_f32 v[38:39], v[46:47], v[98:99]
	v_pk_add_f32 v[42:43], v[102:103], 1.0 op_sel_hi:[1,0]
	v_pk_mul_f32 v[40:41], v[48:49], v[100:101]
	v_pk_add_f32 v[44:45], v[104:105], 1.0 op_sel_hi:[1,0]
	v_pk_fma_f32 v[38:39], v[38:39], v[42:43], v[106:107]
	v_pk_fma_f32 v[40:41], v[40:41], v[44:45], v[108:109]
	v_cvt_pk_bf16_f32 v38, v38, v39
	v_cvt_pk_bf16_f32 v39, v40, v41
	global_store_dwordx2 v[70:71], v[38:39], off offset:1024
	s_nop 0
	v_pk_mul_f32 v[38:39], v[50:51], v[110:111]
	v_pk_add_f32 v[42:43], v[114:115], 1.0 op_sel_hi:[1,0]
	v_pk_mul_f32 v[40:41], v[52:53], v[112:113]
	v_pk_add_f32 v[44:45], v[116:117], 1.0 op_sel_hi:[1,0]
	v_pk_fma_f32 v[38:39], v[38:39], v[42:43], v[118:119]
	v_pk_fma_f32 v[40:41], v[40:41], v[44:45], v[120:121]
	v_cvt_pk_bf16_f32 v38, v38, v39
	v_cvt_pk_bf16_f32 v39, v40, v41
	global_store_dwordx2 v[70:71], v[38:39], off offset:1536
	s_andn2_b64 exec, exec, s[28:29]
	s_cbranch_execnz .LBB0_55
